# prep: adaLN GEMV loop issues its eight weight loads together (counted waits) instead of one serialized round trip each
# speedup vs baseline: 1.0511x; 1.0001x over previous
.LBB0_1267:
	v_lshl_add_u64 v[46:47], v[44:45], 0, s[52:53]
	global_load_dwordx4 v[116:119], v[46:47], off nt
	s_mov_b32 s7, 0x6000
	v_add_co_u32_e64 v148, s[42:43], s7, v46
	s_nop 1
	v_addc_co_u32_e64 v149, s[42:43], 0, v47, s[42:43]
	global_load_dwordx4 v[120:123], v[148:149], off nt
	s_mov_b32 s7, 0xc000
	v_add_co_u32_e64 v148, s[42:43], s7, v46
	s_nop 1
	v_addc_co_u32_e64 v149, s[42:43], 0, v47, s[42:43]
	global_load_dwordx4 v[124:127], v[148:149], off nt
	s_mov_b32 s7, 0x12000
	v_add_co_u32_e64 v148, s[42:43], s7, v46
	s_nop 1
	v_addc_co_u32_e64 v149, s[42:43], 0, v47, s[42:43]
	global_load_dwordx4 v[128:131], v[148:149], off nt
	s_mov_b32 s7, 0x18000
	v_add_co_u32_e64 v148, s[42:43], s7, v46
	s_nop 1
	v_addc_co_u32_e64 v149, s[42:43], 0, v47, s[42:43]
	global_load_dwordx4 v[132:135], v[148:149], off nt
	s_mov_b32 s7, 0x1e000
	v_add_co_u32_e64 v148, s[42:43], s7, v46
	s_nop 1
	v_addc_co_u32_e64 v149, s[42:43], 0, v47, s[42:43]
	global_load_dwordx4 v[136:139], v[148:149], off nt
	s_mov_b32 s7, 0x24000
	v_add_co_u32_e64 v148, s[42:43], s7, v46
	s_nop 1
	v_addc_co_u32_e64 v149, s[42:43], 0, v47, s[42:43]
	global_load_dwordx4 v[140:143], v[148:149], off nt
	s_mov_b32 s7, 0x2a000
	v_add_co_u32_e64 v148, s[42:43], s7, v46
	s_nop 1
	v_addc_co_u32_e64 v149, s[42:43], 0, v47, s[42:43]
	global_load_dwordx4 v[144:147], v[148:149], off nt
	ds_read_b128 v[74:77], v73
	ds_read_b128 v[36:39], v73 offset:16
	s_mov_b32 s7, 0xc000
	s_add_u32 s52, s52, 0x30000
	s_addc_u32 s53, s53, 0
	s_cmp_lg_u32 s52, 0x180000
	s_waitcnt vmcnt(7) lgkmcnt(1)
	v_pk_fma_f32 v[78:79], v[116:117], v[74:75], v[20:21] op_sel_hi:[1,0,1]
	v_pk_fma_f32 v[80:81], v[118:119], v[74:75], v[22:23] op_sel_hi:[1,0,1]
	ds_read_b128 v[20:23], v73 offset:4096
	s_waitcnt lgkmcnt(0)
	v_pk_fma_f32 v[82:83], v[116:117], v[20:21], v[32:33] op_sel_hi:[1,0,1]
	v_pk_fma_f32 v[84:85], v[118:119], v[20:21], v[34:35] op_sel_hi:[1,0,1]
	ds_read_b128 v[32:35], v73 offset:8192
	s_waitcnt lgkmcnt(0)
	v_pk_fma_f32 v[86:87], v[116:117], v[32:33], v[28:29] op_sel_hi:[1,0,1]
	v_pk_fma_f32 v[88:89], v[118:119], v[32:33], v[30:31] op_sel_hi:[1,0,1]
	ds_read_b128 v[28:31], v73 offset:12288
	s_waitcnt lgkmcnt(0)
	v_pk_fma_f32 v[90:91], v[116:117], v[28:29], v[24:25] op_sel_hi:[1,0,1]
	v_pk_fma_f32 v[92:93], v[118:119], v[28:29], v[26:27] op_sel_hi:[1,0,1]
	ds_read_b128 v[24:27], v73 offset:16384
	s_waitcnt lgkmcnt(0)
	v_pk_fma_f32 v[94:95], v[116:117], v[24:25], v[16:17] op_sel_hi:[1,0,1]
	v_pk_fma_f32 v[96:97], v[118:119], v[24:25], v[18:19] op_sel_hi:[1,0,1]
	ds_read_b128 v[16:19], v73 offset:20480
	s_waitcnt lgkmcnt(0)
	v_pk_fma_f32 v[98:99], v[116:117], v[16:17], v[12:13] op_sel_hi:[1,0,1]
	v_pk_fma_f32 v[100:101], v[118:119], v[16:17], v[14:15] op_sel_hi:[1,0,1]
	ds_read_b128 v[12:15], v73 offset:24576
	s_waitcnt lgkmcnt(0)
	v_pk_fma_f32 v[102:103], v[116:117], v[12:13], v[8:9] op_sel_hi:[1,0,1]
	v_pk_fma_f32 v[104:105], v[118:119], v[12:13], v[10:11] op_sel_hi:[1,0,1]
	ds_read_b128 v[8:11], v73 offset:28672
	s_waitcnt lgkmcnt(0)
	v_pk_fma_f32 v[106:107], v[116:117], v[8:9], v[4:5] op_sel_hi:[1,0,1]
	v_pk_fma_f32 v[108:109], v[118:119], v[8:9], v[6:7] op_sel_hi:[1,0,1]
	ds_read_b128 v[4:7], v73 offset:32768
	s_waitcnt lgkmcnt(0)
	v_pk_fma_f32 v[48:49], v[116:117], v[4:5], v[0:1] op_sel_hi:[1,0,1]
	v_pk_fma_f32 v[50:51], v[118:119], v[4:5], v[2:3] op_sel_hi:[1,0,1]
	s_nop 0
	s_waitcnt vmcnt(6)
	v_pk_fma_f32 v[78:79], v[120:121], v[74:75], v[78:79] op_sel:[0,1,0]
	v_pk_fma_f32 v[74:75], v[122:123], v[74:75], v[80:81] op_sel:[0,1,0]
	v_pk_fma_f32 v[80:81], v[120:121], v[20:21], v[82:83] op_sel:[0,1,0]
	v_pk_fma_f32 v[20:21], v[122:123], v[20:21], v[84:85] op_sel:[0,1,0]
	v_pk_fma_f32 v[82:83], v[120:121], v[32:33], v[86:87] op_sel:[0,1,0]
	v_pk_fma_f32 v[32:33], v[122:123], v[32:33], v[88:89] op_sel:[0,1,0]
	v_pk_fma_f32 v[84:85], v[120:121], v[28:29], v[90:91] op_sel:[0,1,0]
	v_pk_fma_f32 v[28:29], v[122:123], v[28:29], v[92:93] op_sel:[0,1,0]
	v_pk_fma_f32 v[86:87], v[120:121], v[24:25], v[94:95] op_sel:[0,1,0]
	v_pk_fma_f32 v[88:89], v[120:121], v[16:17], v[98:99] op_sel:[0,1,0]
	v_pk_fma_f32 v[90:91], v[120:121], v[12:13], v[102:103] op_sel:[0,1,0]
	v_pk_fma_f32 v[92:93], v[120:121], v[8:9], v[106:107] op_sel:[0,1,0]
	v_pk_fma_f32 v[48:49], v[120:121], v[4:5], v[48:49] op_sel:[0,1,0]
	v_pk_fma_f32 v[24:25], v[122:123], v[24:25], v[96:97] op_sel:[0,1,0]
	s_nop 0
	v_pk_fma_f32 v[16:17], v[122:123], v[16:17], v[100:101] op_sel:[0,1,0]
	v_pk_fma_f32 v[12:13], v[122:123], v[12:13], v[104:105] op_sel:[0,1,0]
	v_pk_fma_f32 v[8:9], v[122:123], v[8:9], v[108:109] op_sel:[0,1,0]
	v_pk_fma_f32 v[4:5], v[122:123], v[4:5], v[50:51] op_sel:[0,1,0]
	s_mov_b32 s7, 0x12000
	s_waitcnt vmcnt(5)
	v_pk_fma_f32 v[50:51], v[124:125], v[76:77], v[78:79] op_sel_hi:[1,0,1]
	v_pk_fma_f32 v[78:79], v[124:125], v[22:23], v[80:81] op_sel_hi:[1,0,1]
	v_pk_fma_f32 v[80:81], v[124:125], v[34:35], v[82:83] op_sel_hi:[1,0,1]
	v_pk_fma_f32 v[84:85], v[124:125], v[30:31], v[84:85] op_sel_hi:[1,0,1]
	v_pk_fma_f32 v[86:87], v[124:125], v[26:27], v[86:87] op_sel_hi:[1,0,1]
	v_pk_fma_f32 v[88:89], v[124:125], v[18:19], v[88:89] op_sel_hi:[1,0,1]
	v_pk_fma_f32 v[90:91], v[124:125], v[14:15], v[90:91] op_sel_hi:[1,0,1]
	v_pk_fma_f32 v[92:93], v[124:125], v[10:11], v[92:93] op_sel_hi:[1,0,1]
	v_pk_fma_f32 v[102:103], v[124:125], v[6:7], v[48:49] op_sel_hi:[1,0,1]
	v_pk_fma_f32 v[74:75], v[126:127], v[76:77], v[74:75] op_sel_hi:[1,0,1]
	s_nop 0
	v_pk_fma_f32 v[20:21], v[126:127], v[22:23], v[20:21] op_sel_hi:[1,0,1]
	v_pk_fma_f32 v[82:83], v[126:127], v[34:35], v[32:33] op_sel_hi:[1,0,1]
	v_pk_fma_f32 v[94:95], v[126:127], v[30:31], v[28:29] op_sel_hi:[1,0,1]
	v_pk_fma_f32 v[96:97], v[126:127], v[26:27], v[24:25] op_sel_hi:[1,0,1]
	v_pk_fma_f32 v[16:17], v[126:127], v[18:19], v[16:17] op_sel_hi:[1,0,1]
	v_pk_fma_f32 v[98:99], v[126:127], v[14:15], v[12:13] op_sel_hi:[1,0,1]
	v_pk_fma_f32 v[100:101], v[126:127], v[10:11], v[8:9] op_sel_hi:[1,0,1]
	v_pk_fma_f32 v[104:105], v[126:127], v[6:7], v[4:5] op_sel_hi:[1,0,1]
	v_mov_b32_e32 v4, v77
	v_mov_b32_e32 v6, v7
	s_mov_b32 s7, 0x18000
	s_waitcnt vmcnt(4)
	v_pk_fma_f32 v[76:77], v[128:129], v[4:5], v[50:51] op_sel_hi:[1,0,1]
	v_pk_fma_f32 v[74:75], v[130:131], v[4:5], v[74:75] op_sel_hi:[1,0,1]
	v_mov_b32_e32 v4, v23
	v_pk_fma_f32 v[48:49], v[128:129], v[4:5], v[78:79] op_sel_hi:[1,0,1]
	v_pk_fma_f32 v[50:51], v[130:131], v[4:5], v[20:21] op_sel_hi:[1,0,1]
	v_mov_b32_e32 v4, v35
	v_pk_fma_f32 v[32:33], v[128:129], v[4:5], v[80:81] op_sel_hi:[1,0,1]
	v_pk_fma_f32 v[34:35], v[130:131], v[4:5], v[82:83] op_sel_hi:[1,0,1]
	v_mov_b32_e32 v4, v31
	v_pk_fma_f32 v[28:29], v[128:129], v[4:5], v[84:85] op_sel_hi:[1,0,1]
	v_pk_fma_f32 v[30:31], v[130:131], v[4:5], v[94:95] op_sel_hi:[1,0,1]
	v_mov_b32_e32 v4, v27
	v_pk_fma_f32 v[24:25], v[128:129], v[4:5], v[86:87] op_sel_hi:[1,0,1]
	v_pk_fma_f32 v[26:27], v[130:131], v[4:5], v[96:97] op_sel_hi:[1,0,1]
	v_mov_b32_e32 v4, v19
	v_pk_fma_f32 v[20:21], v[128:129], v[4:5], v[88:89] op_sel_hi:[1,0,1]
	v_pk_fma_f32 v[22:23], v[130:131], v[4:5], v[16:17] op_sel_hi:[1,0,1]
	v_mov_b32_e32 v4, v15
	v_pk_fma_f32 v[12:13], v[128:129], v[4:5], v[90:91] op_sel_hi:[1,0,1]
	v_pk_fma_f32 v[14:15], v[130:131], v[4:5], v[98:99] op_sel_hi:[1,0,1]
	v_mov_b32_e32 v4, v11
	v_pk_fma_f32 v[8:9], v[128:129], v[4:5], v[92:93] op_sel_hi:[1,0,1]
	v_pk_fma_f32 v[10:11], v[130:131], v[4:5], v[100:101] op_sel_hi:[1,0,1]
	v_pk_fma_f32 v[4:5], v[128:129], v[6:7], v[102:103] op_sel_hi:[1,0,1]
	v_pk_fma_f32 v[6:7], v[130:131], v[6:7], v[104:105] op_sel_hi:[1,0,1]
	s_nop 0
	ds_read_b128 v[82:85], v73 offset:16400
	ds_read_b128 v[86:89], v73 offset:20496
	ds_read_b128 v[90:93], v73 offset:24592
	ds_read_b128 v[94:97], v73 offset:28688
	ds_read_b128 v[78:81], v73 offset:12304
	ds_read_b128 v[98:101], v73 offset:32784
	s_mov_b32 s7, 0x1e000
	s_waitcnt vmcnt(3)
	v_pk_fma_f32 v[16:17], v[132:133], v[36:37], v[76:77] op_sel_hi:[1,0,1]
	v_pk_fma_f32 v[18:19], v[134:135], v[36:37], v[74:75] op_sel_hi:[1,0,1]
	ds_read_b128 v[74:77], v73 offset:4112
	s_waitcnt lgkmcnt(2)
	v_pk_fma_f32 v[28:29], v[132:133], v[78:79], v[28:29] op_sel_hi:[1,0,1]
	v_pk_fma_f32 v[24:25], v[132:133], v[82:83], v[24:25] op_sel_hi:[1,0,1]
	v_pk_fma_f32 v[20:21], v[132:133], v[86:87], v[20:21] op_sel_hi:[1,0,1]
	v_pk_fma_f32 v[12:13], v[132:133], v[90:91], v[12:13] op_sel_hi:[1,0,1]
	s_waitcnt lgkmcnt(0)
	v_pk_fma_f32 v[102:103], v[132:133], v[74:75], v[48:49] op_sel_hi:[1,0,1]
	v_pk_fma_f32 v[104:105], v[134:135], v[74:75], v[50:51] op_sel_hi:[1,0,1]
	ds_read_b128 v[48:51], v73 offset:8208
	v_pk_fma_f32 v[8:9], v[132:133], v[94:95], v[8:9] op_sel_hi:[1,0,1]
	v_pk_fma_f32 v[4:5], v[132:133], v[98:99], v[4:5] op_sel_hi:[1,0,1]
	v_pk_fma_f32 v[30:31], v[134:135], v[78:79], v[30:31] op_sel_hi:[1,0,1]
	v_pk_fma_f32 v[26:27], v[134:135], v[82:83], v[26:27] op_sel_hi:[1,0,1]
	s_waitcnt lgkmcnt(0)
	v_pk_fma_f32 v[32:33], v[132:133], v[48:49], v[32:33] op_sel_hi:[1,0,1]
	v_pk_fma_f32 v[34:35], v[134:135], v[48:49], v[34:35] op_sel_hi:[1,0,1]
	s_nop 0
	v_pk_fma_f32 v[22:23], v[134:135], v[86:87], v[22:23] op_sel_hi:[1,0,1]
	v_pk_fma_f32 v[14:15], v[134:135], v[90:91], v[14:15] op_sel_hi:[1,0,1]
	v_pk_fma_f32 v[10:11], v[134:135], v[94:95], v[10:11] op_sel_hi:[1,0,1]
	v_pk_fma_f32 v[6:7], v[134:135], v[98:99], v[6:7] op_sel_hi:[1,0,1]
	s_mov_b32 s7, 0x24000
	v_add_u32_e32 v73, 32, v73
	s_waitcnt vmcnt(2)
	v_pk_fma_f32 v[16:17], v[136:137], v[36:37], v[16:17] op_sel:[0,1,0]
	v_pk_fma_f32 v[18:19], v[138:139], v[36:37], v[18:19] op_sel:[0,1,0]
	v_pk_fma_f32 v[36:37], v[136:137], v[74:75], v[102:103] op_sel:[0,1,0]
	v_pk_fma_f32 v[32:33], v[136:137], v[48:49], v[32:33] op_sel:[0,1,0]
	v_pk_fma_f32 v[28:29], v[136:137], v[78:79], v[28:29] op_sel:[0,1,0]
	v_pk_fma_f32 v[24:25], v[136:137], v[82:83], v[24:25] op_sel:[0,1,0]
	v_pk_fma_f32 v[20:21], v[136:137], v[86:87], v[20:21] op_sel:[0,1,0]
	v_pk_fma_f32 v[12:13], v[136:137], v[90:91], v[12:13] op_sel:[0,1,0]
	v_pk_fma_f32 v[8:9], v[136:137], v[94:95], v[8:9] op_sel:[0,1,0]
	v_pk_fma_f32 v[4:5], v[136:137], v[98:99], v[4:5] op_sel:[0,1,0]
	v_pk_fma_f32 v[74:75], v[138:139], v[74:75], v[104:105] op_sel:[0,1,0]
	s_nop 0
	v_pk_fma_f32 v[34:35], v[138:139], v[48:49], v[34:35] op_sel:[0,1,0]
	v_pk_fma_f32 v[30:31], v[138:139], v[78:79], v[30:31] op_sel:[0,1,0]
	v_pk_fma_f32 v[26:27], v[138:139], v[82:83], v[26:27] op_sel:[0,1,0]
	v_pk_fma_f32 v[22:23], v[138:139], v[86:87], v[22:23] op_sel:[0,1,0]
	v_pk_fma_f32 v[14:15], v[138:139], v[90:91], v[14:15] op_sel:[0,1,0]
	v_pk_fma_f32 v[10:11], v[138:139], v[94:95], v[10:11] op_sel:[0,1,0]
	v_pk_fma_f32 v[6:7], v[138:139], v[98:99], v[6:7] op_sel:[0,1,0]
	s_mov_b32 s7, 0x2a000
	s_waitcnt vmcnt(1)
	v_pk_fma_f32 v[16:17], v[140:141], v[38:39], v[16:17] op_sel_hi:[1,0,1]
	v_pk_fma_f32 v[36:37], v[140:141], v[76:77], v[36:37] op_sel_hi:[1,0,1]
	v_pk_fma_f32 v[48:49], v[142:143], v[76:77], v[74:75] op_sel_hi:[1,0,1]
	v_pk_fma_f32 v[74:75], v[140:141], v[50:51], v[32:33] op_sel_hi:[1,0,1]
	v_pk_fma_f32 v[82:83], v[140:141], v[80:81], v[28:29] op_sel_hi:[1,0,1]
	v_pk_fma_f32 v[90:91], v[140:141], v[84:85], v[24:25] op_sel_hi:[1,0,1]
	v_pk_fma_f32 v[98:99], v[140:141], v[88:89], v[20:21] op_sel_hi:[1,0,1]
	v_pk_fma_f32 v[104:105], v[140:141], v[92:93], v[12:13] op_sel_hi:[1,0,1]
	v_pk_fma_f32 v[108:109], v[140:141], v[96:97], v[8:9] op_sel_hi:[1,0,1]
	v_pk_fma_f32 v[112:113], v[140:141], v[100:101], v[4:5] op_sel_hi:[1,0,1]
	v_pk_fma_f32 v[18:19], v[142:143], v[38:39], v[18:19] op_sel_hi:[1,0,1]
	s_nop 0
	v_pk_fma_f32 v[78:79], v[142:143], v[50:51], v[34:35] op_sel_hi:[1,0,1]
	v_pk_fma_f32 v[86:87], v[142:143], v[80:81], v[30:31] op_sel_hi:[1,0,1]
	v_pk_fma_f32 v[94:95], v[142:143], v[84:85], v[26:27] op_sel_hi:[1,0,1]
	v_pk_fma_f32 v[102:103], v[142:143], v[88:89], v[22:23] op_sel_hi:[1,0,1]
	v_pk_fma_f32 v[106:107], v[142:143], v[92:93], v[14:15] op_sel_hi:[1,0,1]
	v_pk_fma_f32 v[110:111], v[142:143], v[96:97], v[10:11] op_sel_hi:[1,0,1]
	v_pk_fma_f32 v[114:115], v[142:143], v[100:101], v[6:7] op_sel_hi:[1,0,1]
	v_mov_b32_e32 v4, v39
	v_mov_b32_e32 v6, v97
	s_waitcnt vmcnt(0)
	v_pk_fma_f32 v[20:21], v[144:145], v[4:5], v[16:17] op_sel_hi:[1,0,1]
	v_pk_fma_f32 v[22:23], v[146:147], v[4:5], v[18:19] op_sel_hi:[1,0,1]
	v_mov_b32_e32 v4, v77
	v_pk_fma_f32 v[32:33], v[144:145], v[4:5], v[36:37] op_sel_hi:[1,0,1]
	v_pk_fma_f32 v[34:35], v[146:147], v[4:5], v[48:49] op_sel_hi:[1,0,1]
	v_mov_b32_e32 v4, v51
	v_pk_fma_f32 v[28:29], v[144:145], v[4:5], v[74:75] op_sel_hi:[1,0,1]
	v_pk_fma_f32 v[30:31], v[146:147], v[4:5], v[78:79] op_sel_hi:[1,0,1]
	v_mov_b32_e32 v4, v81
	v_pk_fma_f32 v[24:25], v[144:145], v[4:5], v[82:83] op_sel_hi:[1,0,1]
	v_pk_fma_f32 v[26:27], v[146:147], v[4:5], v[86:87] op_sel_hi:[1,0,1]
	v_mov_b32_e32 v4, v85
	v_pk_fma_f32 v[16:17], v[144:145], v[4:5], v[90:91] op_sel_hi:[1,0,1]
	v_pk_fma_f32 v[18:19], v[146:147], v[4:5], v[94:95] op_sel_hi:[1,0,1]
	v_mov_b32_e32 v4, v89
	v_pk_fma_f32 v[12:13], v[144:145], v[4:5], v[98:99] op_sel_hi:[1,0,1]
	v_pk_fma_f32 v[14:15], v[146:147], v[4:5], v[102:103] op_sel_hi:[1,0,1]
	v_mov_b32_e32 v4, v93
	v_mov_b32_e32 v36, v101
	v_pk_fma_f32 v[8:9], v[144:145], v[4:5], v[104:105] op_sel_hi:[1,0,1]
	v_pk_fma_f32 v[10:11], v[146:147], v[4:5], v[106:107] op_sel_hi:[1,0,1]
	v_pk_fma_f32 v[4:5], v[144:145], v[6:7], v[108:109] op_sel_hi:[1,0,1]
	v_pk_fma_f32 v[6:7], v[146:147], v[6:7], v[110:111] op_sel_hi:[1,0,1]
	v_pk_fma_f32 v[0:1], v[144:145], v[36:37], v[112:113] op_sel_hi:[1,0,1]
	v_pk_fma_f32 v[2:3], v[146:147], v[36:37], v[114:115] op_sel_hi:[1,0,1]
	s_cbranch_scc1 .LBB0_1267
	ds_write_b128 v72, v[20:23] offset:36864
	ds_write_b128 v72, v[32:35] offset:37376
	ds_write_b128 v72, v[28:31] offset:37888
	ds_write_b128 v72, v[24:27] offset:38400
	ds_write_b128 v72, v[16:19] offset:38912
	ds_write_b128 v72, v[12:15] offset:39424
	ds_write_b128 v72, v[8:11] offset:39936
	ds_write_b128 v72, v[4:7] offset:40448
	ds_write_b128 v72, v[0:3] offset:40960
	s_waitcnt lgkmcnt(0)
	s_barrier
	s_and_saveexec_b64 s[42:43], s[40:41]
	s_cbranch_execz .LBB0_1258
	v_add_u32_e32 v14, s2, v40
	v_ashrrev_i32_e32 v15, 31, v14
	v_lshl_add_u64 v[0:1], v[14:15], 2, s[50:51]
	global_load_dword v73, v[0:1], off
	ds_read2st64_b32 v[16:17], v54 offset0:144 offset1:146
	ds_read2st64_b32 v[0:1], v54 offset0:160 offset1:162
	ds_read2st64_b32 v[18:19], v54 offset0:180 offset1:182
	ds_read2st64_b32 v[2:3], v54 offset0:196 offset1:198
	ds_read2st64_b32 v[20:21], v54 offset0:216 offset1:218
	ds_read2st64_b32 v[4:5], v54 offset0:232 offset1:234
	ds_read2st64_b32 v[22:23], v54 offset0:252 offset1:254
	ds_read2st64_b32 v[6:7], v55 offset0:124 offset1:126
	ds_read2st64_b32 v[24:25], v55 offset0:144 offset1:146
	ds_read2st64_b32 v[8:9], v55 offset0:160 offset1:162
	ds_read2st64_b32 v[26:27], v55 offset0:180 offset1:182
	ds_read2st64_b32 v[10:11], v55 offset0:196 offset1:198
	ds_read2st64_b32 v[28:29], v55 offset0:216 offset1:218
	ds_read2st64_b32 v[12:13], v55 offset0:232 offset1:234
	ds_read2st64_b32 v[30:31], v55 offset0:252 offset1:254
	ds_read2st64_b32 v[32:33], v54 offset0:164 offset1:166
	ds_read2st64_b32 v[34:35], v54 offset0:200 offset1:202
	ds_read2st64_b32 v[36:37], v54 offset0:236 offset1:238
	ds_read2st64_b32 v[38:39], v55 offset0:128 offset1:130
	ds_read2st64_b32 v[44:45], v55 offset0:164 offset1:166
	ds_read2st64_b32 v[46:47], v55 offset0:200 offset1:202
	ds_read2st64_b32 v[48:49], v55 offset0:236 offset1:238
	ds_read2st64_b32 v[50:51], v54 offset0:148 offset1:150
	ds_read2st64_b32 v[74:75], v54 offset0:184 offset1:186
	ds_read2st64_b32 v[76:77], v54 offset0:220 offset1:222
	ds_read2st64_b32 v[78:79], v55 offset0:112 offset1:114
	ds_read2st64_b32 v[80:81], v55 offset0:148 offset1:150
	ds_read2st64_b32 v[82:83], v55 offset0:184 offset1:186
	ds_read2st64_b32 v[84:85], v55 offset0:220 offset1:222
	ds_read_b32 v90, v56
	ds_read_b32 v91, v57
	ds_read_b32 v92, v58
	ds_read_b32 v93, v59
	ds_read_b32 v94, v60
	ds_read_b32 v95, v61
	ds_read_b32 v96, v62
	ds_read_b32 v97, v63
	s_mov_b32 s2, 0x2aaaaaab
	v_mul_hi_i32 v15, v14, s2
	v_lshrrev_b32_e32 v86, 31, v15
	v_ashrrev_i32_e32 v15, 10, v15
	v_add_u32_e32 v98, v15, v86
	v_mul_i32_i24_e32 v15, 0x1800, v98
	v_sub_u32_e32 v14, v14, v15
	v_ashrrev_i32_e32 v15, 31, v14
	v_mul_i32_i24_e32 v86, 9, v98
	v_lshl_add_u64 v[14:15], v[14:15], 2, s[58:59]
	v_mad_i32_i24 v88, v98, 9, 1
	v_mad_i64_i32 v[86:87], s[28:29], v86, s82, v[14:15]
	v_mad_i64_i32 v[88:89], s[28:29], v88, s82, v[14:15]
	s_waitcnt vmcnt(0) lgkmcnt(14)
	v_add_f32_e32 v16, v73, v16
	v_add_f32_e32 v17, v73, v17
	v_add_f32_e32 v1, v16, v1
	v_add_f32_e32 v16, v17, v32
	v_add_f32_e32 v1, v1, v18
	v_add_f32_e32 v16, v16, v19
	v_add_f32_e32 v1, v1, v3
	v_add_f32_e32 v3, v16, v34
	v_add_f32_e32 v1, v1, v20
	v_add_f32_e32 v50, v73, v50
	v_add_f32_e32 v3, v3, v21
	v_add_f32_e32 v1, v1, v5
	v_add_f32_e32 v17, v50, v33
	v_add_f32_e32 v3, v3, v36
	v_add_f32_e32 v1, v1, v22
	s_waitcnt lgkmcnt(13)
	v_add_f32_e32 v17, v17, v74
	v_add_f32_e32 v3, v3, v23
	v_add_f32_e32 v1, v1, v7
	v_add_f32_e32 v16, v17, v35
	v_add_f32_e32 v3, v3, v38
	v_add_f32_e32 v1, v1, v24
	s_waitcnt lgkmcnt(12)
	v_add_f32_e32 v16, v16, v76
	v_add_f32_e32 v3, v3, v25
	v_add_f32_e32 v1, v1, v9
	v_add_f32_e32 v5, v16, v37
	v_add_f32_e32 v3, v3, v44
	v_add_f32_e32 v1, v1, v26
	s_waitcnt lgkmcnt(11)
	v_add_f32_e32 v5, v5, v78
	v_add_f32_e32 v3, v3, v27
	v_add_f32_e32 v1, v1, v11
	v_add_f32_e32 v5, v5, v39
	v_add_f32_e32 v3, v3, v46
	v_add_f32_e32 v1, v1, v28
	s_waitcnt lgkmcnt(10)
	v_add_f32_e32 v5, v5, v80
	v_add_f32_e32 v3, v3, v29
	v_add_f32_e32 v1, v1, v13
	v_add_f32_e32 v5, v5, v45
	v_add_f32_e32 v3, v3, v48
	v_add_f32_e32 v1, v1, v30
	s_waitcnt lgkmcnt(9)
	v_add_f32_e32 v5, v5, v82
	v_add_f32_e32 v3, v3, v31
	s_waitcnt lgkmcnt(7)
	v_add_f32_e32 v1, v1, v90
	s_waitcnt lgkmcnt(6)
	v_add_f32_e32 v3, v3, v91
	global_store_dword v[86:87], v1, off
	global_store_dword v[88:89], v3, off
	v_add_f32_e32 v1, v5, v47
	v_add_f32_e32 v1, v1, v84
	v_add_f32_e32 v1, v1, v49
	s_waitcnt lgkmcnt(5)
	v_add_f32_e32 v1, v1, v92
	v_mad_i32_i24 v3, v98, 9, 2
	ds_read2st64_b32 v[16:17], v54 offset0:168 offset1:170
	s_waitcnt lgkmcnt(5)
	v_add_f32_e32 v1, v1, v93
	v_mad_i64_i32 v[18:19], s[28:29], v3, s82, v[14:15]
	global_store_dword v[18:19], v1, off
	ds_read2st64_b32 v[18:19], v54 offset0:204 offset1:206
	v_add_f32_e32 v1, v73, v51
	ds_read2st64_b32 v[20:21], v54 offset0:240 offset1:242
	s_waitcnt lgkmcnt(2)
	v_add_f32_e32 v1, v1, v16
	v_add_f32_e32 v1, v1, v75
	ds_read2st64_b32 v[22:23], v55 offset0:132 offset1:134
	s_waitcnt lgkmcnt(2)
	v_add_f32_e32 v1, v1, v18
	v_add_f32_e32 v1, v1, v77
	ds_read2st64_b32 v[24:25], v55 offset0:168 offset1:170
	s_waitcnt lgkmcnt(2)
	v_add_f32_e32 v1, v1, v20
	v_add_f32_e32 v1, v1, v79
	ds_read2st64_b32 v[26:27], v55 offset0:204 offset1:206
	s_waitcnt lgkmcnt(2)
	v_add_f32_e32 v1, v1, v22
	v_add_f32_e32 v1, v1, v81
	ds_read2st64_b32 v[28:29], v55 offset0:240 offset1:242
	s_waitcnt lgkmcnt(2)
	v_add_f32_e32 v1, v1, v24
	v_add_f32_e32 v1, v1, v83
	s_waitcnt lgkmcnt(1)
	v_add_f32_e32 v1, v1, v26
	v_add_f32_e32 v1, v1, v85
	ds_read2st64_b32 v[30:31], v54 offset0:152 offset1:154
	s_waitcnt lgkmcnt(1)
	v_add_f32_e32 v1, v1, v28
	v_add_f32_e32 v1, v1, v94
	v_mad_i32_i24 v3, v98, 9, 3
	ds_read2st64_b32 v[34:35], v54 offset0:188 offset1:190
	v_add_f32_e32 v1, v1, v95
	v_mad_i64_i32 v[32:33], s[28:29], v3, s82, v[14:15]
	global_store_dword v[32:33], v1, off
	ds_read2st64_b32 v[32:33], v54 offset0:224 offset1:226
	s_waitcnt lgkmcnt(2)
	v_add_f32_e32 v1, v73, v30
	v_add_f32_e32 v1, v1, v17
	ds_read2st64_b32 v[16:17], v55 offset0:116 offset1:118
	s_waitcnt lgkmcnt(2)
	v_add_f32_e32 v1, v1, v34
	v_add_f32_e32 v1, v1, v19
	ds_read2st64_b32 v[18:19], v55 offset0:152 offset1:154
	s_waitcnt lgkmcnt(2)
	v_add_f32_e32 v1, v1, v32
	v_add_f32_e32 v1, v1, v21
	ds_read2st64_b32 v[20:21], v55 offset0:188 offset1:190
	s_waitcnt lgkmcnt(2)
	v_add_f32_e32 v1, v1, v16
	v_add_f32_e32 v1, v1, v23
	ds_read2st64_b32 v[22:23], v55 offset0:224 offset1:226
	s_waitcnt lgkmcnt(2)
	v_add_f32_e32 v1, v1, v18
	v_add_f32_e32 v1, v1, v25
	s_waitcnt lgkmcnt(1)
	v_add_f32_e32 v1, v1, v20
	v_add_f32_e32 v1, v1, v27
	s_waitcnt lgkmcnt(0)
	v_add_f32_e32 v1, v1, v22
	v_add_f32_e32 v1, v1, v29
	v_add_f32_e32 v1, v1, v96
	v_mad_i32_i24 v3, v98, 9, 4
	ds_read2st64_b32 v[24:25], v54 offset0:172 offset1:174
	v_add_f32_e32 v1, v1, v97
	v_mad_i64_i32 v[26:27], s[28:29], v3, s82, v[14:15]
	global_store_dword v[26:27], v1, off
	ds_read2st64_b32 v[26:27], v54 offset0:208 offset1:210
	v_add_f32_e32 v1, v73, v31
	ds_read2st64_b32 v[28:29], v54 offset0:244 offset1:246
	s_waitcnt lgkmcnt(2)
	v_add_f32_e32 v1, v1, v24
	v_add_f32_e32 v1, v1, v35
	s_waitcnt lgkmcnt(1)
	v_add_f32_e32 v1, v1, v26
	ds_read2st64_b32 v[30:31], v55 offset0:136 offset1:138
	v_add_f32_e32 v1, v1, v33
	s_waitcnt lgkmcnt(1)
	v_add_f32_e32 v1, v1, v28
	v_add_f32_e32 v1, v1, v17
	ds_read2st64_b32 v[16:17], v55 offset0:172 offset1:174
	ds_read2st64_b32 v[32:33], v55 offset0:208 offset1:210
	s_waitcnt lgkmcnt(2)
	v_add_f32_e32 v1, v1, v30
	v_add_f32_e32 v1, v1, v19
	ds_read2st64_b32 v[18:19], v55 offset0:244 offset1:246
	s_waitcnt lgkmcnt(2)
	v_add_f32_e32 v1, v1, v16
	v_add_f32_e32 v1, v1, v21
	s_waitcnt lgkmcnt(1)
	v_add_f32_e32 v1, v1, v32
	v_add_f32_e32 v1, v1, v23
	ds_read_b32 v3, v64
	ds_read_b32 v5, v65
	ds_read_b32 v7, v66
	ds_read_b32 v9, v67
	ds_read_b32 v11, v68
	ds_read_b32 v13, v69
	ds_read_b32 v36, v70
	ds_read_b32 v37, v71
	ds_read2st64_b32 v[20:21], v54 offset0:156 offset1:158
	s_waitcnt lgkmcnt(9)
	v_add_f32_e32 v1, v1, v18
	s_waitcnt lgkmcnt(8)
	v_add_f32_e32 v1, v1, v3
	v_mad_i32_i24 v3, v98, 9, 5
	ds_read2st64_b32 v[34:35], v54 offset0:192 offset1:194
	s_waitcnt lgkmcnt(8)
	v_add_f32_e32 v1, v1, v5
	v_mad_i64_i32 v[22:23], s[28:29], v3, s82, v[14:15]
	global_store_dword v[22:23], v1, off
	ds_read2st64_b32 v[22:23], v54 offset0:228 offset1:230
	s_waitcnt lgkmcnt(2)
	v_add_f32_e32 v1, v73, v20
	v_add_f32_e32 v1, v1, v25
	ds_read2st64_b32 v[24:25], v55 offset0:120 offset1:122
	s_waitcnt lgkmcnt(2)
	v_add_f32_e32 v1, v1, v34
	v_add_f32_e32 v1, v1, v27
	ds_read2st64_b32 v[26:27], v55 offset0:156 offset1:158
	s_waitcnt lgkmcnt(2)
	v_add_f32_e32 v1, v1, v22
	v_add_f32_e32 v1, v1, v29
	ds_read2st64_b32 v[28:29], v55 offset0:192 offset1:194
	s_waitcnt lgkmcnt(2)
	v_add_f32_e32 v1, v1, v24
	v_add_f32_e32 v1, v1, v31
	ds_read2st64_b32 v[30:31], v55 offset0:228 offset1:230
	s_waitcnt lgkmcnt(2)
	v_add_f32_e32 v1, v1, v26
	v_add_f32_e32 v1, v1, v17
	s_waitcnt lgkmcnt(1)
	v_add_f32_e32 v1, v1, v28
	v_add_f32_e32 v1, v1, v33
	s_waitcnt lgkmcnt(0)
	v_add_f32_e32 v1, v1, v30
	v_add_f32_e32 v1, v1, v19
	v_add_f32_e32 v1, v1, v7
	v_mad_i32_i24 v3, v98, 9, 6
	ds_read2st64_b32 v[16:17], v54 offset0:176 offset1:178
	v_add_f32_e32 v1, v1, v9
	v_mad_i64_i32 v[18:19], s[28:29], v3, s82, v[14:15]
	global_store_dword v[18:19], v1, off
	ds_read2st64_b32 v[18:19], v54 offset0:212 offset1:214
	v_add_f32_e32 v1, v73, v21
	ds_read2st64_b32 v[20:21], v54 offset0:248 offset1:250
	v_add_f32_e32 v0, v73, v0
	s_waitcnt lgkmcnt(2)
	v_add_f32_e32 v1, v1, v16
	v_add_f32_e32 v0, v0, v17
	v_add_f32_e32 v1, v1, v35
	ds_read2st64_b32 v[32:33], v55 offset0:140 offset1:142
	v_add_f32_e32 v0, v0, v2
	s_waitcnt lgkmcnt(2)
	v_add_f32_e32 v1, v1, v18
	v_add_f32_e32 v0, v0, v19
	v_add_f32_e32 v1, v1, v23
	ds_read2st64_b32 v[22:23], v55 offset0:176 offset1:178
	v_add_f32_e32 v0, v0, v4
	s_waitcnt lgkmcnt(2)
	v_add_f32_e32 v1, v1, v20
	v_add_f32_e32 v0, v0, v21
	v_add_f32_e32 v1, v1, v25
	ds_read2st64_b32 v[24:25], v55 offset0:212 offset1:214
	v_add_f32_e32 v0, v0, v6
	s_waitcnt lgkmcnt(2)
	v_add_f32_e32 v1, v1, v32
	v_add_f32_e32 v0, v0, v33
	v_add_f32_e32 v1, v1, v27
	ds_read2st64_b32 v[26:27], v55 offset0:248 offset1:250
	v_add_f32_e32 v0, v0, v8
	s_waitcnt lgkmcnt(2)
	v_add_f32_e32 v1, v1, v22
	v_add_f32_e32 v0, v0, v23
	v_add_f32_e32 v1, v1, v29
	v_add_f32_e32 v0, v0, v10
	s_waitcnt lgkmcnt(1)
	v_add_f32_e32 v1, v1, v24
	v_add_f32_e32 v0, v0, v25
	v_add_f32_e32 v1, v1, v31
	v_add_f32_e32 v0, v0, v12
	s_waitcnt lgkmcnt(0)
	v_add_f32_e32 v1, v1, v26
	v_add_f32_e32 v0, v0, v27
	v_add_f32_e32 v1, v1, v11
	v_mad_i32_i24 v3, v98, 9, 7
	v_add_f32_e32 v0, v0, v36
	v_add_f32_e32 v1, v1, v13
	v_mad_i64_i32 v[28:29], s[28:29], v3, s82, v[14:15]
	v_add_f32_e32 v2, v0, v37
	v_mad_i32_i24 v0, v98, 9, 8
	global_store_dword v[28:29], v1, off
	v_mad_i64_i32 v[0:1], s[28:29], v0, s82, v[14:15]
	global_store_dword v[0:1], v2, off
	s_branch .LBB0_1258
